# v14 + straight-line steady-state copy of both differential-attention tile loops in front of the general loop (no staging branches / condition code for tiles 0..123)
# baseline (speedup 1.0000x reference)
; template <int DQK, int DV>
; __device__ __forceinline__ void attn_pass(const bf16_t* __restrict__ qh, const bf16_t* __restrict__ kh, const bf16_t* __restrict__ vth, int q0, char* smem, f32x16 (&o)[DV / 32], float kmax, int wvp) {
;   constexpr int KP = (DQK + 8) * 2, VP = 144, KSB = 64 * KP, VSB = DV * VP;
;   constexpr int CK = DQK / 8, TKC = 64 * CK, NKC = (TKC + 511) / 512, NVC = DV / 64, NKS = DQK / 16, NEB = DV / 32, NT = S / 64;
;   char* sK = smem; char* sV = smem + 2 * KSB;
;   int tid = wvp * 64 + lane_id(); asm volatile("" : "+v"(tid));
;   const int lane = tid & 63, wid = tid >> 6, r = lane & 31, h = lane >> 5;
;   bf16x8 qf[NKS];
;   {
;     const bf16_t* qrow = qh + (size_t)(q0 + 32 * wid + r) * DQK + 8 * h;
; #pragma unroll
;     for (int ks = 0; ks < NKS; ++ks) qf[ks] = *(const bf16x8*)(qrow + 16 * ks);
;   }
;   int klo[NKC], vlo[NVC];
;   const bf16_t* vg0 = vth + (size_t)(tid >> 3) * S + (tid & 7) * 8;
;   const bool k1 = (TKC % 512 == 0) || (tid < TKC % 512);
; #pragma unroll
;   for (int j = 0; j < NKC; ++j) { const int c = tid + 512 * j; klo[j] = (c / CK) * KP + (c % CK) * 16; }
; #pragma unroll
;   for (int j = 0; j < NVC; ++j) { const int c = tid + 512 * j; vlo[j] = (c >> 3) * VP + (c & 7) * 16; }
;   u32x4 rk[NKC], rv[NVC], rk1[NKC];
;   const int rot = (int)((blockIdx.x >> 3) * 4u) & (NT - 1);
;     ...
;   LOADK(rk, 0); LOADV(rv, 0); LOADK(rk1, 1);
; #pragma unroll
;   for (int eb = 0; eb < NEB; ++eb)
; #pragma unroll
;     for (int i = 0; i < 16; ++i) o[eb][i] = 0.f;
;   float l_run = 0.f;
;   f32x16 negm;
;   {
;     float qq = 0.f;
; #pragma unroll
;     for (int ks = 0; ks < NKS; ++ks)
; #pragma unroll
;       for (int j = 0; j < 8; ++j) { const float t = bf2f((unsigned short)qf[ks][j]); qq += t * t; }
; __global__ void __launch_bounds__(512, 2) mega_fwd(Params p_arg) {
;     ...
;         for (int u = blockIdx.x; u < 256; u += G) {
;           const int bh = u & 7, qt = u >> 3, bb = bh >> 2, hd = bh & 3;
;           const bf16_t* vth = vtb + (size_t)(bb * 4 + hd) * 128 * S;
;           f32x16 o[4];
;           const int tok = bb * S + qt * 256 + 32 * wid + r;
;           bf16_t* dst = mix + (size_t)tok * DM + 512 + hd * 128;
;           attn_pass<64, 128>(qb + (size_t)(bb * 8 + hd * 2) * S * 64, kb + (size_t)(bb * 8 + hd * 2) * S * 64, vth, qt * 256, smem, o, kmax_of(kmx, bb * 8 + hd * 2), wv);
.LBB0_575:
	s_lshl_b32 s4, s36, 21
	s_bfe_u32 s50, s36, 0x10002
	s_and_b32 s45, s36, 3
	s_and_b32 s4, s4, 0xe00000
	s_add_u32 s12, s48, s4
	s_addc_u32 s13, s49, 0
	s_lshl_b32 s4, s36, 5
	s_and_b32 s37, s4, 0xffffff00
	s_lshl_b32 s4, s50, 3
	s_lshl_b32 s5, s45, 1
	s_or_b32 s44, s4, s5
	s_lshl_b32 s6, s44, 20
	s_add_u32 s4, s86, s6
	s_addc_u32 s5, s87, 0
	s_add_u32 s6, s88, s6
	s_addc_u32 s7, s89, 0
	s_lshl_b32 s8, s44, 2
	v_mov_b32_e32 v0, s8
	global_load_dword v12, v0, s[46:47]
	global_load_dword v13, v0, s[46:47] offset:256
	global_load_dword v14, v0, s[46:47] offset:512
	global_load_dword v15, v0, s[46:47] offset:768
	global_load_dword v18, v0, s[46:47] offset:1024
	global_load_dword v19, v0, s[46:47] offset:1280
	global_load_dword v20, v0, s[46:47] offset:1536
	global_load_dword v21, v0, s[46:47] offset:1792
	v_mbcnt_lo_u32_b32 v0, -1, 0
	v_mbcnt_hi_u32_b32 v0, -1, v0
	s_mov_b32 s51, s2
	v_add_u32_e32 v0, s27, v0
	s_mov_b32 s52, s1
	v_and_b32_e32 v32, 31, v0
	v_ashrrev_i32_e32 v1, 1, v0
	v_and_b32_e32 v1, 0xffffffe0, v1
	v_or_b32_e32 v2, s37, v32
	v_add_u32_e32 v2, v2, v1
	v_ashrrev_i32_e32 v3, 31, v2
	v_lshlrev_b64 v[2:3], 7, v[2:3]
	v_lshrrev_b32_e32 v28, 1, v0
	v_lshl_add_u64 v[2:3], s[4:5], 0, v[2:3]
	v_and_b32_e32 v208, 16, v28
	v_lshl_add_u64 v[4:5], v[2:3], 0, v[208:209]
	global_load_dwordx4 v[176:179], v[4:5], off
	global_load_dwordx4 v[180:183], v[4:5], off offset:32
	global_load_dwordx4 v[184:187], v[4:5], off offset:64
	global_load_dwordx4 v[188:191], v[4:5], off offset:96
	v_ashrrev_i32_e32 v6, 3, v0
	v_ashrrev_i32_e32 v1, 31, v0
	v_lshlrev_b32_e32 v2, 4, v0
	v_add_u32_e32 v3, 0x200, v0
	v_ashrrev_i32_e32 v7, 31, v6
	s_add_u32 s4, s6, s21
	v_lshrrev_b32_e32 v9, 29, v1
	v_and_b32_e32 v8, 0x70, v2
	v_lshrrev_b32_e32 v16, 3, v3
	v_lshlrev_b64 v[10:11], 14, v[6:7]
	s_addc_u32 s5, s7, 0
	v_lshlrev_b64 v[2:3], 4, v[0:1]
	v_add_u32_e32 v1, v0, v9
	v_mad_u64_u32 v[210:211], s[16:17], v6, s20, v[8:9]
	v_mad_u64_u32 v[212:213], s[16:17], v16, s20, v[8:9]
	v_mov_b32_e32 v9, v209
	v_lshl_add_u64 v[6:7], s[12:13], 0, v[10:11]
	v_lshl_add_u64 v[22:23], s[4:5], 0, v[2:3]
	v_lshl_add_u64 v[214:215], v[6:7], 0, v[8:9]
	v_add_co_u32_e32 v16, vcc, s23, v22
	v_lshl_add_u64 v[24:25], v[214:215], 0, s[10:11]
	s_nop 0
	v_addc_co_u32_e32 v17, vcc, 0, v23, vcc
	v_add_co_u32_e64 v26, s[4:5], s22, v24
	global_load_dwordx4 v[4:7], v[22:23], off
	global_load_dwordx4 v[8:11], v[24:25], off
	v_addc_co_u32_e64 v27, s[4:5], 0, v25, s[4:5]
	v_lshrrev_b32_e32 v29, 3, v1
	v_and_b32_e32 v1, 0xffffff8, v1
	v_sub_u32_e32 v1, v0, v1
	v_mul_lo_u32 v29, v29, s20
	v_lshl_add_u32 v211, v1, 4, v29
	v_and_b32_e32 v1, 19, v0
	v_lshlrev_b32_e32 v0, 1, v0
	v_and_b32_e32 v0, 8, v0
	v_lshl_add_u64 v[216:217], s[6:7], 0, v[2:3]
	v_mov_b32_e32 v218, 0
	s_mov_b32 s53, s9
	v_mov_b32_e32 v2, v209
	v_mov_b32_e32 v3, v209
	v_mov_b32_e32 v40, v209
	v_mov_b32_e32 v41, v209
	v_mov_b32_e32 v42, v209
	v_mov_b32_e32 v43, v209
	v_mov_b32_e32 v44, v209
	v_mov_b32_e32 v45, v209
	v_mov_b32_e32 v46, v209
	v_mov_b32_e32 v47, v209
	v_mov_b32_e32 v48, 0
	v_mov_b32_e32 v49, v209
	s_waitcnt vmcnt(12)
	v_max_u32_e32 v12, v12, v13
	v_mov_b32_e32 v50, v209
	s_waitcnt vmcnt(10)
	v_max3_u32 v12, v12, v14, v15
	v_mov_b32_e32 v51, v209
	s_waitcnt vmcnt(8)
	v_max3_u32 v12, v12, v18, v19
	v_mov_b32_e32 v52, v209
	s_waitcnt vmcnt(6)
	v_max3_u32 v12, v12, v20, v21
	v_mul_f32_e32 v13, 0x4f800000, v12
	v_cmp_gt_f32_e32 vcc, s3, v12
	v_mov_b32_e32 v53, v209
	v_mov_b32_e32 v54, v209
	v_cndmask_b32_e32 v30, v12, v13, vcc
	global_load_dwordx4 v[12:15], v[26:27], off
	global_load_dwordx4 v[18:21], v[16:17], off
	v_sqrt_f32_e32 v31, v30
	s_barrier
	v_add_u32_e32 v16, -1, v31
	v_add_u32_e32 v17, 1, v31
	v_fma_f32 v38, -v16, v31, v30
	v_fma_f32 v39, -v17, v31, v30
	v_cmp_ge_f32_e64 s[4:5], 0, v38
	s_waitcnt vmcnt(7)
	v_and_b32_e32 v34, 0xffff0000, v176
	v_lshlrev_b32_e32 v33, 16, v176
	v_mul_f32_e32 v34, v34, v34
	v_cndmask_b32_e64 v16, v31, v16, s[4:5]
	v_cmp_lt_f32_e64 s[4:5], 0, v39
	v_lshlrev_b32_e32 v35, 16, v177
	v_fmac_f32_e32 v34, v33, v33
	v_cndmask_b32_e64 v16, v16, v17, s[4:5]
	v_and_b32_e32 v36, 0xffff0000, v177
	v_fmac_f32_e32 v34, v35, v35
	v_mul_f32_e32 v17, 0x37800000, v16
	v_lshlrev_b32_e32 v37, 16, v178
	v_fmac_f32_e32 v34, v36, v36
	v_cndmask_b32_e32 v16, v16, v17, vcc
	v_cmp_class_f32_e32 vcc, v30, v220
	v_fmac_f32_e32 v34, v37, v37
	s_waitcnt vmcnt(4)
	v_and_b32_e32 v17, 0xffff0000, v191
	v_cndmask_b32_e32 v30, v16, v30, vcc
	v_and_b32_e32 v16, 0xffff0000, v178
	v_fmac_f32_e32 v34, v16, v16
	v_lshlrev_b32_e32 v16, 16, v179
	v_fmac_f32_e32 v34, v16, v16
	v_and_b32_e32 v16, 0xffff0000, v179
	v_fmac_f32_e32 v34, v16, v16
	v_lshlrev_b32_e32 v16, 16, v180
	v_fmac_f32_e32 v34, v16, v16
	v_and_b32_e32 v16, 0xffff0000, v180
	v_fmac_f32_e32 v34, v16, v16
	v_lshlrev_b32_e32 v16, 16, v181
	v_fmac_f32_e32 v34, v16, v16
	v_and_b32_e32 v16, 0xffff0000, v181
	v_fmac_f32_e32 v34, v16, v16
	v_lshlrev_b32_e32 v16, 16, v182
	v_fmac_f32_e32 v34, v16, v16
	v_and_b32_e32 v16, 0xffff0000, v182
	v_fmac_f32_e32 v34, v16, v16
	v_lshlrev_b32_e32 v16, 16, v183
	v_fmac_f32_e32 v34, v16, v16
	v_and_b32_e32 v16, 0xffff0000, v183
	v_fmac_f32_e32 v34, v16, v16
	v_lshlrev_b32_e32 v16, 16, v184
	v_fmac_f32_e32 v34, v16, v16
	v_and_b32_e32 v16, 0xffff0000, v184
	v_fmac_f32_e32 v34, v16, v16
	v_lshlrev_b32_e32 v16, 16, v185
	v_fmac_f32_e32 v34, v16, v16
	v_and_b32_e32 v16, 0xffff0000, v185
	v_fmac_f32_e32 v34, v16, v16
	v_lshlrev_b32_e32 v16, 16, v186
	v_fmac_f32_e32 v34, v16, v16
	v_and_b32_e32 v16, 0xffff0000, v186
	v_fmac_f32_e32 v34, v16, v16
	v_lshlrev_b32_e32 v16, 16, v187
	v_fmac_f32_e32 v34, v16, v16
	v_and_b32_e32 v16, 0xffff0000, v187
	v_fmac_f32_e32 v34, v16, v16
	v_lshlrev_b32_e32 v16, 16, v188
	v_fmac_f32_e32 v34, v16, v16
	v_and_b32_e32 v16, 0xffff0000, v188
	v_fmac_f32_e32 v34, v16, v16
	v_lshlrev_b32_e32 v16, 16, v189
	v_fmac_f32_e32 v34, v16, v16
	v_and_b32_e32 v16, 0xffff0000, v189
	v_fmac_f32_e32 v34, v16, v16
	v_lshlrev_b32_e32 v16, 16, v190
	v_fmac_f32_e32 v34, v16, v16
	v_and_b32_e32 v16, 0xffff0000, v190
	v_fmac_f32_e32 v34, v16, v16
	v_lshlrev_b32_e32 v16, 16, v191
	v_pk_mul_f32 v[16:17], v[16:17], v[16:17]
	s_waitcnt vmcnt(3)
; __device__ __forceinline__ int swz23(int r) { return (r & ~12) | ((r & 4) << 1) | ((r & 8) >> 1); }
; #define LOADK(dst, t) do { _Pragma("unroll") for (int j = 0; j < NKC; ++j) if (j == 0 || k1) dst[j] = *(const u32x4*)(kh + (size_t)(((t) + rot) & (NT - 1)) * 64 * DQK + (size_t)(tid + 512 * j) * 8); } while (0)
; #define LOADV(dst, t) do { _Pragma("unroll") for (int j = 0; j < NVC; ++j) dst[j] = *(const u32x4*)(vg0 + (size_t)(64 * j) * S + (size_t)(((t) + rot) & (NT - 1)) * 64); } while (0)
; #define STOREK(src, slot) do { _Pragma("unroll") for (int j = 0; j < NKC; ++j) if (j == 0 || k1) *(u32x4*)(sK + (slot) * KSB + klo[j]) = src[j]; } while (0)
; #define STOREV(src, slot) do { _Pragma("unroll") for (int j = 0; j < NVC; ++j) *(u32x4*)(sV + (slot) * VSB + vlo[j]) = src[j]; } while (0)
; template <int DQK, int DV>
; __device__ __forceinline__ void attn_pass(const bf16_t* __restrict__ qh, const bf16_t* __restrict__ kh, const bf16_t* __restrict__ vth, int q0, char* smem, f32x16 (&o)[DV / 32], float kmax, int wvp) {
;     ...
;   for (int eb = 0; eb < NEB; ++eb)
; #pragma unroll
;     for (int i = 0; i < 16; ++i) o[eb][i] = 0.f;
;   float l_run = 0.f;
;   f32x16 negm;
;   {
;     float qq = 0.f;
; #pragma unroll
;     for (int ks = 0; ks < NKS; ++ks)
; #pragma unroll
;       for (int j = 0; j < 8; ++j) { const float t = bf2f((unsigned short)qf[ks][j]); qq += t * t; }
;     { auto rr = __builtin_amdgcn_permlane32_swap(__float_as_uint(qq), __float_as_uint(qq), false, false); qq = __uint_as_float(rr[0]) + __uint_as_float(rr[1]); }
;     const float mref = sqrtf(qq) * kmax * 1.01f + 0.01f;
; #pragma unroll
;     for (int i = 0; i < 16; ++i) negm[i] = -mref;
;   }
;   __syncthreads();
;   STOREK(rk, 0); STOREV(rv, 0); STOREK(rk1, 1);
;   LOADK(rk, 2); LOADV(rv, 1);
;   const int kofs = swz23(r) * KP + 16 * h, vofs = r * VP + 16 * h;
;   __syncthreads();
;   f32x16 sA, sB;
;     ...
;   f32x16 sA0, sA1, sB0, sB1;
;   QKT(sA, 0);
	ds_write_b128 v211, v[4:7]
	s_waitcnt vmcnt(2)
	ds_write_b128 v210, v[8:11] offset:18432
	s_waitcnt vmcnt(1)
	ds_write_b128 v212, v[12:15] offset:18432
	s_waitcnt vmcnt(0)
	ds_write_b128 v211, v[18:21] offset:9216
	v_add_f32_e32 v16, v16, v34
	v_add_f32_e32 v16, v17, v16
	v_mov_b32_e32 v17, v16
	s_nop 1
	v_permlane32_swap_b32_e32 v16, v17
	v_add_f32_e32 v16, v16, v17
	v_mul_f32_e32 v17, 0x4f800000, v16
	v_cmp_gt_f32_e32 vcc, s3, v16
	v_mov_b32_e32 v34, v209
	v_mov_b32_e32 v35, v209
	v_cndmask_b32_e32 v16, v16, v17, vcc
	v_sqrt_f32_e32 v17, v16
	v_mov_b32_e32 v36, v209
	v_mov_b32_e32 v37, v209
	v_mov_b32_e32 v38, v209
	v_add_u32_e32 v31, -1, v17
	v_fma_f32 v33, -v31, v17, v16
	v_cmp_ge_f32_e64 s[4:5], 0, v33
	v_add_u32_e32 v33, 1, v17
	v_mov_b32_e32 v39, v209
	v_cndmask_b32_e64 v31, v17, v31, s[4:5]
	v_fma_f32 v17, -v33, v17, v16
	v_cmp_lt_f32_e64 s[4:5], 0, v17
	v_mov_b32_e32 v55, v209
	v_mov_b32_e32 v56, v209
	v_cndmask_b32_e64 v17, v31, v33, s[4:5]
	v_mul_f32_e32 v31, 0x37800000, v17
	v_cndmask_b32_e32 v17, v17, v31, vcc
	v_cmp_class_f32_e32 vcc, v16, v220
	v_mov_b32_e32 v33, v209
	v_mov_b32_e32 v57, v209
	v_cndmask_b32_e32 v16, v17, v16, vcc
	v_add_co_u32_e32 v4, vcc, s0, v22
	v_mul_f32_e32 v16, v30, v16
	s_nop 0
	v_addc_co_u32_e32 v5, vcc, 0, v23, vcc
	global_load_dwordx4 v[192:195], v[4:5], off
	global_load_dwordx4 v[196:199], v[24:25], off offset:128
	global_load_dwordx4 v[200:203], v[26:27], off offset:128
	v_and_b32_e32 v4, 4, v28
	v_or3_b32 v0, v1, v0, v4
	v_mad_u32_u24 v213, v0, s20, v208
	s_waitcnt lgkmcnt(0)
	s_barrier
	ds_read_b128 v[4:7], v213
	ds_read_b128 v[8:11], v213 offset:32
	v_fmamk_f32 v16, v16, 0x3f8147ae, v221
	v_xor_b32_e32 v16, 0x80000000, v16
	v_mov_b32_e32 v17, v16
	v_mov_b32_e32 v18, v16
	v_mov_b32_e32 v19, v16
	v_mov_b32_e32 v20, v16
	v_mov_b32_e32 v21, v16
	v_mov_b32_e32 v22, v16
	v_mov_b32_e32 v23, v16
	v_mov_b32_e32 v24, v16
	v_mov_b32_e32 v25, v16
	v_mov_b32_e32 v26, v16
	v_mov_b32_e32 v27, v16
	v_mov_b32_e32 v28, v16
	v_mov_b32_e32 v29, v16
	v_mov_b32_e32 v30, v16
	v_mov_b32_e32 v31, v16
	v_mad_u32_u24 v208, v32, s20, v208
	v_mov_b32_e32 v0, 0
	s_waitcnt lgkmcnt(1)
	v_mfma_f32_32x32x16_bf16 v[96:111], v[4:7], v[176:179], v[16:31]
	ds_read_b128 v[4:7], v213 offset:4608
	ds_read_b128 v[12:15], v213 offset:4640
	v_mov_b32_e32 v1, v209
	v_mov_b32_e32 v32, 0
	v_mov_b32_e32 v58, v209
	v_mov_b32_e32 v59, v209
	v_mov_b32_e32 v60, v209
	v_mov_b32_e32 v61, v209
	s_waitcnt lgkmcnt(2)
	v_mfma_f32_32x32x16_bf16 v[96:111], v[8:11], v[180:183], v[96:111]
	v_mov_b32_e32 v62, v209
	v_mov_b32_e32 v63, v209
	v_mov_b32_e32 v64, 0
	v_mov_b32_e32 v65, v209
	v_mov_b32_e32 v66, v209
	v_mov_b32_e32 v67, v209
	v_mov_b32_e32 v68, v209
	s_waitcnt lgkmcnt(1)
	v_mfma_f32_32x32x16_bf16 v[80:95], v[4:7], v[176:179], v[16:31]
	ds_read_b128 v[4:7], v213 offset:64
	ds_read_b128 v[8:11], v213 offset:96
	v_mov_b32_e32 v69, v209
	v_mov_b32_e32 v70, v209
	v_mov_b32_e32 v71, v209
	v_mov_b32_e32 v72, v209
	v_mov_b32_e32 v73, v209
	v_mov_b32_e32 v74, v209
	s_waitcnt lgkmcnt(1)
	v_mfma_f32_32x32x16_bf16 v[96:111], v[4:7], v[184:187], v[96:111]
	v_mov_b32_e32 v75, v209
	v_mov_b32_e32 v76, v209
	v_mov_b32_e32 v77, v209
	v_mov_b32_e32 v78, v209
	v_mov_b32_e32 v79, v209
	v_mfma_f32_32x32x16_bf16 v[80:95], v[12:15], v[180:183], v[80:95]
	v_mov_b32_e32 v12, v209
	v_mov_b32_e32 v13, v209
	v_mov_b32_e32 v14, v209
	v_mov_b32_e32 v15, v209
	s_waitcnt lgkmcnt(0)
	v_mfma_f32_32x32x16_bf16 v[96:111], v[8:11], v[188:191], v[96:111]
	ds_read_b128 v[4:7], v213 offset:4672
	ds_read_b128 v[8:11], v213 offset:4704
	s_waitcnt lgkmcnt(1)
	v_mfma_f32_32x32x16_bf16 v[80:95], v[4:7], v[184:187], v[80:95]
	v_mov_b32_e32 v4, v209
	v_mov_b32_e32 v5, v209
	v_mov_b32_e32 v6, v209
	v_mov_b32_e32 v7, v209
	s_waitcnt lgkmcnt(0)
	v_mfma_f32_32x32x16_bf16 v[80:95], v[8:11], v[188:191], v[80:95]
	v_mov_b32_e32 v8, v209
	v_mov_b32_e32 v9, v209
	v_mov_b32_e32 v10, v209
	v_mov_b32_e32 v11, v209
	s_cmpk_lt_u32 s53, 0x7c
	s_cbranch_scc0 .LBB0_578
.Lfast_e1:
	s_barrier
	s_waitcnt vmcnt(0)
	ds_write_b128 v211, v[192:195]
	s_waitcnt vmcnt(1)
	ds_write_b128 v210, v[196:199] offset:36864
	s_waitcnt vmcnt(0)
	ds_write_b128 v212, v[200:203] offset:36864
	s_add_i32 s4, s52, 0xfffff000
	s_and_b32 s4, s4, 0x7f000
	s_lshl_b32 s8, s4, 1
	v_lshl_add_u64 v[112:113], v[216:217], 0, s[8:9]
	global_load_dwordx4 v[192:195], v[112:113], off
	s_sub_i32 s6, s51, 64
	s_and_b32 s6, s6, 0x1f80
	s_lshl_b32 s8, s6, 1
	v_lshl_add_u64 v[112:113], v[214:215], 0, s[8:9]
	v_add_co_u32_e32 v114, vcc, 0x100000, v112
	s_nop 1
	v_addc_co_u32_e32 v115, vcc, 0, v113, vcc
	global_load_dwordx4 v[196:199], v[112:113], off
	global_load_dwordx4 v[200:203], v[114:115], off
	ds_read_b128 v[112:115], v213 offset:9216
	ds_read_b128 v[128:131], v213 offset:9248
	ds_read_b128 v[132:135], v213 offset:13824
	ds_read_b128 v[136:139], v213 offset:13856
	v_exp_f32_e32 v172, v92
	v_exp_f32_e32 v173, v93
	s_waitcnt lgkmcnt(3)
	v_mfma_f32_32x32x16_bf16 v[144:159], v[112:115], v[176:179], v[16:31]
	v_exp_f32_e32 v174, v94
	v_exp_f32_e32 v175, v95
	s_waitcnt lgkmcnt(2)
	v_mfma_f32_32x32x16_bf16 v[144:159], v[128:131], v[180:183], v[144:159]
	s_waitcnt lgkmcnt(1)
	v_mfma_f32_32x32x16_bf16 v[112:127], v[132:135], v[176:179], v[16:31]
	ds_read_b128 v[128:131], v213 offset:9280
	ds_read_b128 v[132:135], v213 offset:9312
	ds_read_b128 v[140:143], v213 offset:13888
	ds_read_b128 v[228:231], v213 offset:13920
	ds_read_b128 v[160:163], v208 offset:18464
	s_waitcnt lgkmcnt(4)
	v_mfma_f32_32x32x16_bf16 v[144:159], v[128:131], v[184:187], v[144:159]
	v_exp_f32_e32 v128, v96
	v_exp_f32_e32 v129, v97
	v_exp_f32_e32 v130, v98
	v_exp_f32_e32 v131, v99
	ds_read_b128 v[96:99], v208 offset:18432
	s_waitcnt lgkmcnt(4)
; template <int DQK, int DV>
; __device__ __forceinline__ void attn_pass(const bf16_t* __restrict__ qh, const bf16_t* __restrict__ kh, const bf16_t* __restrict__ vth, int q0, char* smem, f32x16 (&o)[DV / 32], float kmax, int wvp) {
;     ...
; #pragma unroll
;   for (int ks = 0; ks < NKS; ++ks) asm volatile("" :: "v"(qf[ks]));
; #pragma unroll 1
;   for (int kt = 0; kt < NT; kt += 2) {
;     STEP(sA, sB, kt);
;     STEP(sB, sA, kt + 1);
	v_mfma_f32_32x32x16_bf16 v[144:159], v[132:135], v[188:191], v[144:159]
	v_exp_f32_e32 v132, v100
	v_exp_f32_e32 v133, v101
	v_exp_f32_e32 v134, v102
	v_exp_f32_e32 v135, v103
	v_cvt_pk_bf16_f32 v100, v128, v129
	v_cvt_pk_bf16_f32 v101, v130, v131
	v_cvt_pk_bf16_f32 v102, v132, v133
	v_cvt_pk_bf16_f32 v103, v134, v135
	v_mfma_f32_32x32x16_bf16 v[112:127], v[136:139], v[180:183], v[112:127]
	v_exp_f32_e32 v136, v104
	v_exp_f32_e32 v137, v105
	v_exp_f32_e32 v138, v106
	v_exp_f32_e32 v139, v107
	s_waitcnt lgkmcnt(0)
	v_mfma_f32_32x32x16_bf16 v[64:79], v[96:99], v[100:103], v[64:79]
	ds_read_b128 v[96:99], v208 offset:23040
	ds_read_b128 v[164:167], v208 offset:23072
	s_waitcnt lgkmcnt(1)
	v_mfma_f32_32x32x16_bf16 v[48:63], v[96:99], v[100:103], v[48:63]
	ds_read_b128 v[96:99], v208 offset:27648
	ds_read_b128 v[168:171], v208 offset:27680
	ds_read_b128 v[104:107], v208 offset:32288
	s_waitcnt lgkmcnt(2)
	v_mfma_f32_32x32x16_bf16 v[32:47], v[96:99], v[100:103], v[32:47]
	ds_read_b128 v[96:99], v208 offset:32256
	v_mfma_f32_32x32x16_bf16 v[112:127], v[140:143], v[184:187], v[112:127]
	v_exp_f32_e32 v140, v108
	v_exp_f32_e32 v141, v109
	v_exp_f32_e32 v142, v110
	v_exp_f32_e32 v143, v111
	s_waitcnt lgkmcnt(0)
	v_mfma_f32_32x32x16_bf16 v[0:15], v[96:99], v[100:103], v[0:15]
	v_cvt_pk_bf16_f32 v96, v136, v137
	v_cvt_pk_bf16_f32 v97, v138, v139
	v_cvt_pk_bf16_f32 v98, v140, v141
	v_cvt_pk_bf16_f32 v99, v142, v143
	s_nop 1
	v_mfma_f32_32x32x16_bf16 v[64:79], v[160:163], v[96:99], v[64:79]
	v_exp_f32_e32 v160, v80
	v_exp_f32_e32 v161, v81
	v_exp_f32_e32 v162, v82
	v_exp_f32_e32 v163, v83
	ds_read_b128 v[80:83], v208 offset:18496
	v_mfma_f32_32x32x16_bf16 v[48:63], v[164:167], v[96:99], v[48:63]
	v_exp_f32_e32 v164, v84
	v_exp_f32_e32 v165, v85
	v_exp_f32_e32 v166, v86
	v_exp_f32_e32 v167, v87
	v_cvt_pk_bf16_f32 v84, v160, v161
	v_cvt_pk_bf16_f32 v85, v162, v163
	v_cvt_pk_bf16_f32 v86, v164, v165
	v_cvt_pk_bf16_f32 v87, v166, v167
	v_mfma_f32_32x32x16_bf16 v[32:47], v[168:171], v[96:99], v[32:47]
	v_exp_f32_e32 v168, v88
	v_exp_f32_e32 v169, v89
	v_exp_f32_e32 v170, v90
	v_exp_f32_e32 v171, v91
	v_mfma_f32_32x32x16_bf16 v[0:15], v[104:107], v[96:99], v[0:15]
	ds_read_b128 v[96:99], v208 offset:18528
	s_waitcnt lgkmcnt(1)
	v_mfma_f32_32x32x16_bf16 v[64:79], v[80:83], v[84:87], v[64:79]
	ds_read_b128 v[80:83], v208 offset:23104
	ds_read_b128 v[100:103], v208 offset:23136
	s_waitcnt lgkmcnt(1)
	v_mfma_f32_32x32x16_bf16 v[48:63], v[80:83], v[84:87], v[48:63]
	ds_read_b128 v[80:83], v208 offset:27712
	ds_read_b128 v[104:107], v208 offset:27744
	ds_read_b128 v[88:91], v208 offset:32352
	s_waitcnt lgkmcnt(2)
	v_mfma_f32_32x32x16_bf16 v[32:47], v[80:83], v[84:87], v[32:47]
	ds_read_b128 v[80:83], v208 offset:32320
	s_waitcnt lgkmcnt(0)
	s_barrier
	v_mfma_f32_32x32x16_bf16 v[0:15], v[80:83], v[84:87], v[0:15]
	v_cvt_pk_bf16_f32 v80, v168, v169
	v_cvt_pk_bf16_f32 v81, v170, v171
	v_cvt_pk_bf16_f32 v82, v172, v173
	v_cvt_pk_bf16_f32 v83, v174, v175
	s_nop 1
	v_mfma_f32_32x32x16_bf16 v[64:79], v[96:99], v[80:83], v[64:79]
	v_mfma_f32_32x32x16_bf16 v[48:63], v[100:103], v[80:83], v[48:63]
	v_mfma_f32_32x32x16_bf16 v[32:47], v[104:107], v[80:83], v[32:47]
	v_mfma_f32_32x32x16_bf16 v[0:15], v[88:91], v[80:83], v[0:15]
	v_mfma_f32_32x32x16_bf16 v[112:127], v[228:231], v[188:191], v[112:127]
	s_waitcnt vmcnt(0)
	ds_write_b128 v211, v[192:195] offset:9216
	s_waitcnt vmcnt(1)
	ds_write_b128 v210, v[196:199] offset:18432
	s_waitcnt vmcnt(0)
	ds_write_b128 v212, v[200:203] offset:18432
	s_and_b32 s8, s52, 0x7e000
	s_lshl_b32 s8, s8, 1
	v_lshl_add_u64 v[80:81], v[216:217], 0, s[8:9]
	global_load_dwordx4 v[192:195], v[80:81], off
	s_and_b32 s6, s51, 0x1fc0
	s_lshl_b32 s8, s6, 1
	v_lshl_add_u64 v[80:81], v[214:215], 0, s[8:9]
	v_add_co_u32_e32 v82, vcc, 0x100000, v80
	s_nop 1
	v_addc_co_u32_e32 v83, vcc, 0, v81, vcc
	global_load_dwordx4 v[196:199], v[80:81], off
	global_load_dwordx4 v[200:203], v[82:83], off
	ds_read_b128 v[80:83], v213
	ds_read_b128 v[228:231], v213 offset:32
	ds_read_b128 v[232:235], v213 offset:4608
	ds_read_b128 v[236:239], v213 offset:4640
	s_waitcnt lgkmcnt(3)
	v_mfma_f32_32x32x16_bf16 v[96:111], v[80:83], v[176:179], v[16:31]
	s_waitcnt lgkmcnt(1)
	v_mfma_f32_32x32x16_bf16 v[80:95], v[232:235], v[176:179], v[16:31]
	v_mfma_f32_32x32x16_bf16 v[96:111], v[228:231], v[180:183], v[96:111]
	ds_read_b128 v[228:231], v213 offset:64
	ds_read_b128 v[232:235], v213 offset:96
	s_waitcnt lgkmcnt(2)
	v_mfma_f32_32x32x16_bf16 v[80:95], v[236:239], v[180:183], v[80:95]
	s_waitcnt lgkmcnt(1)
	v_mfma_f32_32x32x16_bf16 v[96:111], v[228:231], v[184:187], v[96:111]
	ds_read_b128 v[228:231], v213 offset:4672
	ds_read_b128 v[236:239], v213 offset:4704
	s_waitcnt lgkmcnt(1)
	v_mfma_f32_32x32x16_bf16 v[80:95], v[228:231], v[184:187], v[80:95]
	v_mfma_f32_32x32x16_bf16 v[96:111], v[232:235], v[188:191], v[96:111]
	s_waitcnt lgkmcnt(0)
	v_mfma_f32_32x32x16_bf16 v[80:95], v[236:239], v[188:191], v[80:95]
	v_exp_f32_e32 v219, v144
	v_exp_f32_e32 v225, v145
	v_exp_f32_e32 v227, v146
	v_exp_f32_e32 v248, v147
	ds_read_b128 v[144:147], v208 offset:36864
	v_exp_f32_e32 v240, v148
	v_exp_f32_e32 v242, v149
	v_exp_f32_e32 v244, v150
	v_exp_f32_e32 v246, v151
	v_cvt_pk_bf16_f32 v148, v219, v225
	v_cvt_pk_bf16_f32 v149, v227, v248
	v_cvt_pk_bf16_f32 v150, v240, v242
	v_cvt_pk_bf16_f32 v151, v244, v246
	ds_read_b128 v[228:231], v208 offset:36896
	ds_read_b128 v[232:235], v208 offset:41472
	s_waitcnt lgkmcnt(2)
; template <int DQK, int DV>
; __device__ __forceinline__ void attn_pass(const bf16_t* __restrict__ qh, const bf16_t* __restrict__ kh, const bf16_t* __restrict__ vth, int q0, char* smem, f32x16 (&o)[DV / 32], float kmax, int wvp) {
;     ...
; #pragma unroll
;   for (int ks = 0; ks < NKS; ++ks) asm volatile("" :: "v"(qf[ks]));
; #pragma unroll 1
;   for (int kt = 0; kt < NT; kt += 2) {
;     STEP(sA, sB, kt);
;     STEP(sB, sA, kt + 1);
;   }
	v_mfma_f32_32x32x16_bf16 v[64:79], v[144:147], v[148:151], v[64:79]
	v_add_f32_e32 v128, v129, v128
	v_add_f32_e32 v129, v161, v160
	ds_read_b128 v[144:147], v208 offset:46080
	ds_read_b128 v[236:239], v208 offset:41504
	v_add_f32_e32 v128, v130, v128
	v_add_f32_e32 v129, v162, v129
	v_add_f32_e32 v128, v131, v128
	v_add_f32_e32 v129, v163, v129
	s_waitcnt lgkmcnt(2)
	v_mfma_f32_32x32x16_bf16 v[48:63], v[232:235], v[148:151], v[48:63]
	v_add_f32_e32 v132, v132, v128
	v_add_f32_e32 v233, v164, v129
	ds_read_b128 v[128:131], v208 offset:50688
	ds_read_b128 v[160:163], v208 offset:46112
	v_exp_f32_e32 v152, v152
	v_exp_f32_e32 v164, v153
	v_exp_f32_e32 v154, v154
	v_exp_f32_e32 v232, v155
	s_waitcnt lgkmcnt(3)
	v_mfma_f32_32x32x16_bf16 v[32:47], v[144:147], v[148:151], v[32:47]
	v_exp_f32_e32 v156, v156
	ds_read_b128 v[144:147], v208 offset:50720
	v_add_f32_e32 v132, v133, v132
	v_add_f32_e32 v133, v165, v233
	v_add_f32_e32 v133, v166, v133
	v_exp_f32_e32 v166, v112
	v_add_f32_e32 v132, v134, v132
	s_waitcnt lgkmcnt(2)
	v_mfma_f32_32x32x16_bf16 v[0:15], v[128:131], v[148:151], v[0:15]
	v_exp_f32_e32 v148, v157
	v_exp_f32_e32 v150, v158
	v_exp_f32_e32 v158, v159
	v_cvt_pk_bf16_f32 v128, v152, v164
	v_cvt_pk_bf16_f32 v129, v154, v232
	v_cvt_pk_bf16_f32 v130, v156, v148
	v_cvt_pk_bf16_f32 v131, v150, v158
	v_add_f32_e32 v132, v135, v132
	v_add_f32_e32 v133, v167, v133
	s_waitcnt lgkmcnt(1)
	v_mfma_f32_32x32x16_bf16 v[32:47], v[160:163], v[128:131], v[32:47]
	v_exp_f32_e32 v160, v113
	v_exp_f32_e32 v161, v114
	v_exp_f32_e32 v162, v115
	ds_read_b128 v[112:115], v208 offset:36928
	v_add_f32_e32 v132, v136, v132
	v_add_f32_e32 v133, v168, v133
	v_exp_f32_e32 v241, v116
	v_mfma_f32_32x32x16_bf16 v[64:79], v[228:231], v[128:131], v[64:79]
	v_exp_f32_e32 v243, v117
	v_exp_f32_e32 v245, v118
	v_exp_f32_e32 v247, v119
	v_add_f32_e32 v132, v137, v132
	v_add_f32_e32 v133, v169, v133
	v_add_f32_e32 v132, v138, v132
	v_add_f32_e32 v133, v170, v133
	v_mfma_f32_32x32x16_bf16 v[48:63], v[236:239], v[128:131], v[48:63]
	v_add_f32_e32 v136, v139, v132
	v_add_f32_e32 v137, v171, v133
	v_cvt_pk_bf16_f32 v116, v166, v160
	v_cvt_pk_bf16_f32 v117, v161, v162
	v_cvt_pk_bf16_f32 v118, v241, v243
	v_cvt_pk_bf16_f32 v119, v245, v247
	v_exp_f32_e32 v153, v120
	s_waitcnt lgkmcnt(1)
	v_mfma_f32_32x32x16_bf16 v[0:15], v[144:147], v[128:131], v[0:15]
	ds_read_b128 v[128:131], v208 offset:41536
	ds_read_b128 v[132:135], v208 offset:36960
	v_exp_f32_e32 v165, v121
	v_add_f32_e32 v120, v225, v219
	v_add_f32_e32 v121, v160, v166
	v_add_f32_e32 v120, v227, v120
	s_waitcnt lgkmcnt(2)
	v_mfma_f32_32x32x16_bf16 v[64:79], v[112:115], v[116:119], v[64:79]
	v_add_f32_e32 v112, v140, v136
	v_add_f32_e32 v113, v172, v137
	v_add_f32_e32 v112, v141, v112
	v_add_f32_e32 v140, v173, v113
	v_add_f32_e32 v141, v142, v112
	ds_read_b128 v[112:115], v208 offset:46144
	ds_read_b128 v[136:139], v208 offset:41568
	v_add_f32_e32 v121, v161, v121
	s_waitcnt lgkmcnt(3)
	v_mfma_f32_32x32x16_bf16 v[48:63], v[128:131], v[116:119], v[48:63]
	v_add_f32_e32 v128, v174, v140
	v_add_f32_e32 v129, v143, v141
	v_add_f32_e32 v128, v175, v128
	v_add_f32_e32 v128, v129, v128
	v_add_f32_e32 v144, v218, v128
	ds_read_b128 v[128:131], v208 offset:50752
	ds_read_b128 v[140:143], v208 offset:46176
	v_add_f32_e32 v120, v248, v120
	s_waitcnt lgkmcnt(3)
	v_mfma_f32_32x32x16_bf16 v[32:47], v[112:115], v[116:119], v[32:47]
	ds_read_b128 v[112:115], v208 offset:50784
	v_add_f32_e32 v121, v162, v121
	v_add_f32_e64 v120, v240, v120
	v_add_f32_e64 v121, v241, v121
	v_exp_f32_e32 v155, v122
	v_exp_f32_e32 v233, v123
	v_exp_f32_e32 v157, v124
	v_exp_f32_e32 v149, v125
	s_waitcnt lgkmcnt(2)
	v_mfma_f32_32x32x16_bf16 v[0:15], v[128:131], v[116:119], v[0:15]
	v_exp_f32_e32 v151, v126
	v_exp_f32_e32 v159, v127
	v_add_f32_e32 v120, v242, v120
	v_add_f32_e32 v121, v243, v121
	v_cvt_pk_bf16_f32 v116, v153, v165
	v_add_f32_e32 v120, v244, v120
	v_add_f32_e32 v121, v245, v121
	v_cvt_pk_bf16_f32 v117, v155, v233
	v_add_f32_e32 v120, v246, v120
	v_add_f32_e32 v121, v247, v121
	v_cvt_pk_bf16_f32 v118, v157, v149
	v_add_f32_e32 v120, v152, v120
	v_add_f32_e32 v121, v153, v121
	v_cvt_pk_bf16_f32 v119, v151, v159
	v_add_f32_e32 v120, v164, v120
	v_add_f32_e32 v121, v165, v121
	s_add_i32 s53, s53, 2
	v_mfma_f32_32x32x16_bf16 v[64:79], v[132:135], v[116:119], v[64:79]
	v_add_f32_e64 v120, v154, v120
	v_add_f32_e64 v121, v155, v121
	s_addk_i32 s52, 0x2000
	v_add_f32_e64 v120, v232, v120
	v_add_f32_e64 v121, v233, v121
	v_add_f32_e32 v120, v156, v120
	v_add_f32_e32 v121, v157, v121
	s_addk_i32 s51, 0x80
	v_add_f32_e32 v120, v148, v120
	v_add_f32_e32 v121, v149, v121
	v_mfma_f32_32x32x16_bf16 v[48:63], v[136:139], v[116:119], v[48:63]
	v_add_f32_e64 v120, v150, v120
	v_add_f32_e64 v121, v151, v121
	v_add_f32_e64 v120, v158, v120
	v_add_f32_e64 v121, v159, v121
	v_add_f32_e32 v120, v120, v121
	v_add_f32_e32 v218, v144, v120
	s_waitcnt lgkmcnt(1)
	v_mfma_f32_32x32x16_bf16 v[32:47], v[140:143], v[116:119], v[32:47]
	s_waitcnt lgkmcnt(0)
	v_mfma_f32_32x32x16_bf16 v[0:15], v[112:115], v[116:119], v[0:15]
	s_cmpk_lt_u32 s53, 0x7c
	s_cbranch_scc1 .Lfast_e1
	s_branch .LBB0_578

; __device__ __forceinline__ unsigned pk2(float lo, float hi) { f32x2_t v = {lo, hi}; bf16x2_t b = __builtin_convertvector(v, bf16x2_t); return __builtin_bit_cast(unsigned, b); }
; __device__ __forceinline__ float frcp(float x) { return __builtin_amdgcn_rcpf(x); }
; template <int DQK, int DV>
; __device__ __forceinline__ void attn_pass(const bf16_t* __restrict__ qh, const bf16_t* __restrict__ kh, const bf16_t* __restrict__ vth, int q0, char* smem, f32x16 (&o)[DV / 32], float kmax, int wvp) {
;     ...
;   float ltot;
;   { auto rr = __builtin_amdgcn_permlane32_swap(__float_as_uint(l_run), __float_as_uint(l_run), false, false); ltot = __uint_as_float(rr[0]) + __uint_as_float(rr[1]); }
;   const float linv = frcp(ltot);
; #pragma unroll
;   for (int eb = 0; eb < NEB; ++eb)
; #pragma unroll
;     for (int i = 0; i < 16; ++i) o[eb][i] *= linv;
; __global__ void __launch_bounds__(512, 2) mega_fwd(Params p_arg) {
;     ...
;           attn_pass<64, 128>(qb + (size_t)(bb * 8 + hd * 2) * S * 64, kb + (size_t)(bb * 8 + hd * 2) * S * 64, vth, qt * 256, smem, o, kmax_of(kmx, bb * 8 + hd * 2), wv);
; #pragma unroll
;           for (int eb = 0; eb < 4; ++eb)
; #pragma unroll
;             for (int i4 = 0; i4 < 4; ++i4) { u32x2 w; w.x = pk2(o[eb][4 * i4], o[eb][4 * i4 + 1]); w.y = pk2(o[eb][4 * i4 + 2], o[eb][4 * i4 + 3]); *(u32x2*)(dst + 32 * eb + 8 * i4 + 4 * h) = w; }
;           attn_pass<64, 128>(qb + (size_t)(bb * 8 + hd * 2 + 1) * S * 64, kb + (size_t)(bb * 8 + hd * 2 + 1) * S * 64, vth, qt * 256, smem, o, kmax_of(kmx, bb * 8 + hd * 2 + 1), wv);
.LBB0_594:
	v_mov_b32_e32 v18, v218
	s_lshl_b32 s4, s50, 13
	s_nop 0
	v_permlane32_swap_b32_e32 v218, v18
	s_add_i32 s4, s4, s37
	v_add_f32_e32 v18, v218, v18
	v_add_u32_e32 v16, s4, v207
	v_rcp_f32_e32 v18, v18
	v_ashrrev_i32_e32 v17, 31, v16
	v_lshlrev_b64 v[16:17], 11, v[16:17]
	v_lshl_add_u64 v[16:17], s[30:31], 0, v[16:17]
	s_lshl_b32 s8, s45, 8
	v_lshl_add_u64 v[16:17], v[16:17], 0, s[8:9]
	v_pk_mul_f32 v[20:21], v[64:65], v[18:19] op_sel_hi:[1,0]
	v_pk_mul_f32 v[22:23], v[66:67], v[18:19] op_sel_hi:[1,0]
	v_lshlrev_b32_e32 v208, 1, v206
	v_pk_mul_f32 v[24:25], v[68:69], v[18:19] op_sel_hi:[1,0]
	v_pk_mul_f32 v[26:27], v[70:71], v[18:19] op_sel_hi:[1,0]
	v_lshl_add_u64 v[210:211], v[16:17], 0, v[208:209]
	v_cvt_pk_bf16_f32 v16, v20, v21
	v_cvt_pk_bf16_f32 v17, v22, v23
	v_pk_mul_f32 v[28:29], v[72:73], v[18:19] op_sel_hi:[1,0]
	v_pk_mul_f32 v[30:31], v[74:75], v[18:19] op_sel_hi:[1,0]
	global_store_dwordx2 v[210:211], v[16:17], off offset:1024
	v_cvt_pk_bf16_f32 v16, v24, v25
	v_cvt_pk_bf16_f32 v17, v26, v27
	v_pk_mul_f32 v[64:65], v[76:77], v[18:19] op_sel_hi:[1,0]
	v_pk_mul_f32 v[66:67], v[78:79], v[18:19] op_sel_hi:[1,0]
	global_store_dwordx2 v[210:211], v[16:17], off offset:1040
	v_cvt_pk_bf16_f32 v16, v28, v29
	v_cvt_pk_bf16_f32 v17, v30, v31
	v_pk_mul_f32 v[48:49], v[48:49], v[18:19] op_sel_hi:[1,0]
	v_pk_mul_f32 v[50:51], v[50:51], v[18:19] op_sel_hi:[1,0]
	global_store_dwordx2 v[210:211], v[16:17], off offset:1056
	v_cvt_pk_bf16_f32 v16, v64, v65
	v_cvt_pk_bf16_f32 v17, v66, v67
	v_pk_mul_f32 v[52:53], v[52:53], v[18:19] op_sel_hi:[1,0]
	v_pk_mul_f32 v[54:55], v[54:55], v[18:19] op_sel_hi:[1,0]
	global_store_dwordx2 v[210:211], v[16:17], off offset:1072
	v_cvt_pk_bf16_f32 v16, v48, v49
	v_cvt_pk_bf16_f32 v17, v50, v51
	v_pk_mul_f32 v[56:57], v[56:57], v[18:19] op_sel_hi:[1,0]
	v_pk_mul_f32 v[58:59], v[58:59], v[18:19] op_sel_hi:[1,0]
	global_store_dwordx2 v[210:211], v[16:17], off offset:1088
	v_cvt_pk_bf16_f32 v16, v52, v53
	v_cvt_pk_bf16_f32 v17, v54, v55
	v_pk_mul_f32 v[60:61], v[60:61], v[18:19] op_sel_hi:[1,0]
	v_pk_mul_f32 v[62:63], v[62:63], v[18:19] op_sel_hi:[1,0]
	global_store_dwordx2 v[210:211], v[16:17], off offset:1104
	v_cvt_pk_bf16_f32 v16, v56, v57
	v_cvt_pk_bf16_f32 v17, v58, v59
	s_or_b32 s8, s44, 1
	v_pk_mul_f32 v[32:33], v[32:33], v[18:19] op_sel_hi:[1,0]
	v_pk_mul_f32 v[34:35], v[34:35], v[18:19] op_sel_hi:[1,0]
	v_pk_mul_f32 v[0:1], v[0:1], v[18:19] op_sel_hi:[1,0]
	v_pk_mul_f32 v[2:3], v[2:3], v[18:19] op_sel_hi:[1,0]
	global_store_dwordx2 v[210:211], v[16:17], off offset:1120
	v_cvt_pk_bf16_f32 v16, v60, v61
	v_cvt_pk_bf16_f32 v17, v62, v63
	s_lshl_b32 s6, s8, 20
	v_pk_mul_f32 v[36:37], v[36:37], v[18:19] op_sel_hi:[1,0]
	v_pk_mul_f32 v[38:39], v[38:39], v[18:19] op_sel_hi:[1,0]
	v_pk_mul_f32 v[4:5], v[4:5], v[18:19] op_sel_hi:[1,0]
	v_pk_mul_f32 v[6:7], v[6:7], v[18:19] op_sel_hi:[1,0]
	global_store_dwordx2 v[210:211], v[16:17], off offset:1136
	v_cvt_pk_bf16_f32 v16, v32, v33
	v_cvt_pk_bf16_f32 v17, v34, v35
	v_cvt_pk_bf16_f32 v0, v0, v1
	v_cvt_pk_bf16_f32 v1, v2, v3
	s_add_u32 s4, s86, s6
	v_pk_mul_f32 v[40:41], v[40:41], v[18:19] op_sel_hi:[1,0]
	v_pk_mul_f32 v[42:43], v[42:43], v[18:19] op_sel_hi:[1,0]
	v_pk_mul_f32 v[8:9], v[8:9], v[18:19] op_sel_hi:[1,0]
	v_pk_mul_f32 v[10:11], v[10:11], v[18:19] op_sel_hi:[1,0]
	global_store_dwordx2 v[210:211], v[16:17], off offset:1152
	v_cvt_pk_bf16_f32 v16, v36, v37
	v_cvt_pk_bf16_f32 v17, v38, v39
	global_store_dwordx2 v[210:211], v[0:1], off offset:1216
	v_cvt_pk_bf16_f32 v0, v4, v5
	v_cvt_pk_bf16_f32 v1, v6, v7
	s_addc_u32 s5, s87, 0
	v_pk_mul_f32 v[44:45], v[44:45], v[18:19] op_sel_hi:[1,0]
	v_pk_mul_f32 v[46:47], v[46:47], v[18:19] op_sel_hi:[1,0]
	v_pk_mul_f32 v[12:13], v[12:13], v[18:19] op_sel_hi:[1,0]
	v_pk_mul_f32 v[14:15], v[14:15], v[18:19] op_sel_hi:[1,0]
	global_store_dwordx2 v[210:211], v[16:17], off offset:1168
	v_cvt_pk_bf16_f32 v16, v40, v41
	v_cvt_pk_bf16_f32 v17, v42, v43
	global_store_dwordx2 v[210:211], v[0:1], off offset:1232
	v_cvt_pk_bf16_f32 v0, v8, v9
	v_cvt_pk_bf16_f32 v1, v10, v11
	s_add_u32 s6, s88, s6
	global_store_dwordx2 v[210:211], v[16:17], off offset:1184
	v_cvt_pk_bf16_f32 v16, v44, v45
	v_cvt_pk_bf16_f32 v17, v46, v47
	global_store_dwordx2 v[210:211], v[0:1], off offset:1248
	v_cvt_pk_bf16_f32 v0, v12, v13
	v_cvt_pk_bf16_f32 v1, v14, v15
	s_addc_u32 s7, s89, 0
	s_lshl_b32 s8, s8, 2
	global_store_dwordx2 v[210:211], v[16:17], off offset:1200
	global_store_dwordx2 v[210:211], v[0:1], off offset:1264
	v_mov_b32_e32 v0, s8
	global_load_dword v2, v0, s[46:47]
	global_load_dword v3, v0, s[46:47] offset:256
	global_load_dword v4, v0, s[46:47] offset:512
	global_load_dword v5, v0, s[46:47] offset:768
	global_load_dword v6, v0, s[46:47] offset:1024
	global_load_dword v7, v0, s[46:47] offset:1280
	global_load_dword v8, v0, s[46:47] offset:1536
	global_load_dword v9, v0, s[46:47] offset:1792
	v_mbcnt_lo_u32_b32 v0, -1, 0
	v_mbcnt_hi_u32_b32 v0, -1, v0
	s_mov_b32 s18, 0
	v_add_u32_e32 v16, s27, v0
	s_mov_b32 s19, s2
	v_and_b32_e32 v28, 31, v16
	v_ashrrev_i32_e32 v0, 1, v16
	v_and_b32_e32 v0, 0xffffffe0, v0
	v_or_b32_e32 v1, s37, v28
	v_add_u32_e32 v0, v1, v0
	v_ashrrev_i32_e32 v1, 31, v0
	v_lshlrev_b64 v[0:1], 7, v[0:1]
	v_lshrrev_b32_e32 v29, 1, v16
	v_lshl_add_u64 v[0:1], s[4:5], 0, v[0:1]
	v_and_b32_e32 v208, 16, v29
	v_lshl_add_u64 v[0:1], v[0:1], 0, v[208:209]
	global_load_dwordx4 v[176:179], v[0:1], off
	global_load_dwordx4 v[180:183], v[0:1], off offset:32
	global_load_dwordx4 v[184:187], v[0:1], off offset:64
	global_load_dwordx4 v[188:191], v[0:1], off offset:96
	v_ashrrev_i32_e32 v0, 3, v16
	v_ashrrev_i32_e32 v1, 31, v0
	v_ashrrev_i32_e32 v17, 31, v16
	v_lshlrev_b64 v[18:19], 4, v[16:17]
	v_lshl_add_u64 v[218:219], s[6:7], 0, v[18:19]
	s_mov_b32 s37, s1
	v_mov_b32_e32 v48, 0
	s_waitcnt vmcnt(10)
; __device__ __forceinline__ int lane_id() { int l; asm volatile("v_mbcnt_lo_u32_b32 %0, -1, 0\n\tv_mbcnt_hi_u32_b32 %0, -1, %0" : "=v"(l)); return l; }
; __device__ __forceinline__ int swz23(int r) { return (r & ~12) | ((r & 4) << 1) | ((r & 8) >> 1); }
; #pragma unroll
;   for (int sl = 0; sl < 8; ++sl) m = max(m, kmx[sl * 64 + idx]);
;   return sqrtf(__uint_as_float(m)); }
; template <int DQK, int DV>
; __device__ __forceinline__ void attn_pass(const bf16_t* __restrict__ qh, const bf16_t* __restrict__ kh, const bf16_t* __restrict__ vth, int q0, char* smem, f32x16 (&o)[DV / 32], float kmax, int wvp) {
;     ...
;   int tid = wvp * 64 + lane_id(); asm volatile("" : "+v"(tid));
;   const int lane = tid & 63, wid = tid >> 6, r = lane & 31, h = lane >> 5;
;   bf16x8 qf[NKS];
;   {
;     const bf16_t* qrow = qh + (size_t)(q0 + 32 * wid + r) * DQK + 8 * h;
; #pragma unroll
;     for (int ks = 0; ks < NKS; ++ks) qf[ks] = *(const bf16x8*)(qrow + 16 * ks);
;   }
;   int klo[NKC], vlo[NVC];
;   const bf16_t* vg0 = vth + (size_t)(tid >> 3) * S + (tid & 7) * 8;
;   const bool k1 = (TKC % 512 == 0) || (tid < TKC % 512);
; #pragma unroll
;   for (int j = 0; j < NKC; ++j) { const int c = tid + 512 * j; klo[j] = (c / CK) * KP + (c % CK) * 16; }
; #pragma unroll
;   for (int j = 0; j < NVC; ++j) { const int c = tid + 512 * j; vlo[j] = (c >> 3) * VP + (c & 7) * 16; }
;   u32x4 rk[NKC], rv[NVC], rk1[NKC];
;   const int rot = (int)((blockIdx.x >> 3) * 4u) & (NT - 1);
;     ...
;   LOADK(rk, 0); LOADV(rv, 0); LOADK(rk1, 1);
; #pragma unroll
;   for (int eb = 0; eb < NEB; ++eb)
; #pragma unroll
;     for (int i = 0; i < 16; ++i) o[eb][i] = 0.f;
;   float l_run = 0.f;
;   f32x16 negm;
;   {
;     float qq = 0.f;
; #pragma unroll
;     for (int ks = 0; ks < NKS; ++ks)
; #pragma unroll
;       for (int j = 0; j < 8; ++j) { const float t = bf2f((unsigned short)qf[ks][j]); qq += t * t; }
;     { auto rr = __builtin_amdgcn_permlane32_swap(__float_as_uint(qq), __float_as_uint(qq), false, false); qq = __uint_as_float(rr[0]) + __uint_as_float(rr[1]); }
;     const float mref = sqrtf(qq) * kmax * 1.01f + 0.01f;
; #pragma unroll
;     for (int i = 0; i < 16; ++i) negm[i] = -mref;
;   }
;   __syncthreads();
;   STOREK(rk, 0); STOREV(rv, 0); STOREK(rk1, 1);
;   LOADK(rk, 2); LOADV(rv, 1);
;   const int kofs = swz23(r) * KP + 16 * h, vofs = r * VP + 16 * h;
;   __syncthreads();
	v_max_u32_e32 v2, v2, v3
	s_waitcnt vmcnt(8)
	v_max3_u32 v2, v2, v4, v5
	s_waitcnt vmcnt(6)
	v_max3_u32 v2, v2, v6, v7
	s_waitcnt vmcnt(4)
	v_max3_u32 v2, v2, v8, v9
	v_mul_f32_e32 v3, 0x4f800000, v2
	v_cmp_gt_f32_e32 vcc, s3, v2
	s_waitcnt vmcnt(3)
	v_and_b32_e32 v26, 0xffff0000, v176
	v_cndmask_b32_e32 v2, v2, v3, vcc
	v_sqrt_f32_e32 v3, v2
	v_mul_f32_e32 v33, v26, v26
	s_waitcnt vmcnt(0)
	v_and_b32_e32 v27, 0xffff0000, v191
	v_lshlrev_b32_e32 v26, 16, v191
	v_add_u32_e32 v4, -1, v3
	v_fma_f32 v5, -v4, v3, v2
	v_cmp_ge_f32_e64 s[4:5], 0, v5
	v_add_u32_e32 v5, 1, v3
	v_pk_mul_f32 v[26:27], v[26:27], v[26:27]
	v_cndmask_b32_e64 v4, v3, v4, s[4:5]
	v_fma_f32 v3, -v5, v3, v2
	v_cmp_lt_f32_e64 s[4:5], 0, v3
	s_nop 1
	v_cndmask_b32_e64 v3, v4, v5, s[4:5]
	v_mul_f32_e32 v4, 0x37800000, v3
	v_cndmask_b32_e32 v3, v3, v4, vcc
	v_cmp_class_f32_e32 vcc, v2, v220
	s_nop 1
	v_cndmask_b32_e32 v30, v3, v2, vcc
	v_lshlrev_b64 v[2:3], 14, v[0:1]
	v_lshrrev_b32_e32 v1, 29, v17
	v_add_u32_e32 v31, v16, v1
	v_lshlrev_b32_e32 v1, 4, v16
	v_and_b32_e32 v4, 0x70, v1
	v_mad_u64_u32 v[212:213], s[4:5], v0, s20, v[4:5]
	v_add_u32_e32 v0, 0x200, v16
	v_lshrrev_b32_e32 v0, 3, v0
	v_mad_u64_u32 v[214:215], s[4:5], v0, s20, v[4:5]
	v_lshl_add_u64 v[0:1], s[12:13], 0, v[2:3]
	v_mov_b32_e32 v5, v209
	v_lshl_add_u64 v[216:217], v[0:1], 0, v[4:5]
	s_add_u32 s4, s6, s21
	v_lshl_add_u64 v[22:23], v[216:217], 0, s[10:11]
	s_addc_u32 s5, s7, 0
	v_add_co_u32_e32 v24, vcc, s22, v22
	v_lshl_add_u64 v[20:21], s[4:5], 0, v[18:19]
	s_nop 0
	v_addc_co_u32_e32 v25, vcc, 0, v23, vcc
	v_add_co_u32_e32 v12, vcc, s23, v20
	global_load_dwordx4 v[0:3], v[20:21], off
	global_load_dwordx4 v[4:7], v[22:23], off
	v_addc_co_u32_e32 v13, vcc, 0, v21, vcc
	global_load_dwordx4 v[8:11], v[24:25], off
	s_nop 0
	global_load_dwordx4 v[12:15], v[12:13], off
	v_lshlrev_b32_e32 v17, 16, v176
	v_fmac_f32_e32 v33, v17, v17
	v_lshlrev_b32_e32 v17, 16, v177
	v_fmac_f32_e32 v33, v17, v17
	v_and_b32_e32 v17, 0xffff0000, v177
	v_fmac_f32_e32 v33, v17, v17
	v_lshlrev_b32_e32 v17, 16, v178
	v_fmac_f32_e32 v33, v17, v17
	v_and_b32_e32 v17, 0xffff0000, v178
	v_fmac_f32_e32 v33, v17, v17
	v_lshlrev_b32_e32 v17, 16, v179
	v_fmac_f32_e32 v33, v17, v17
	v_and_b32_e32 v17, 0xffff0000, v179
	v_fmac_f32_e32 v33, v17, v17
	v_lshlrev_b32_e32 v17, 16, v180
	v_fmac_f32_e32 v33, v17, v17
	v_and_b32_e32 v17, 0xffff0000, v180
	v_fmac_f32_e32 v33, v17, v17
	v_lshlrev_b32_e32 v17, 16, v181
	v_fmac_f32_e32 v33, v17, v17
	v_and_b32_e32 v17, 0xffff0000, v181
	v_fmac_f32_e32 v33, v17, v17
	v_lshlrev_b32_e32 v17, 16, v182
	v_fmac_f32_e32 v33, v17, v17
	v_and_b32_e32 v17, 0xffff0000, v182
	v_fmac_f32_e32 v33, v17, v17
	v_lshlrev_b32_e32 v17, 16, v183
	v_fmac_f32_e32 v33, v17, v17
	v_and_b32_e32 v17, 0xffff0000, v183
	v_fmac_f32_e32 v33, v17, v17
	v_lshlrev_b32_e32 v17, 16, v184
	v_fmac_f32_e32 v33, v17, v17
	v_and_b32_e32 v17, 0xffff0000, v184
	v_fmac_f32_e32 v33, v17, v17
	v_lshlrev_b32_e32 v17, 16, v185
	v_fmac_f32_e32 v33, v17, v17
	v_and_b32_e32 v17, 0xffff0000, v185
	v_fmac_f32_e32 v33, v17, v17
	v_lshlrev_b32_e32 v17, 16, v186
	v_fmac_f32_e32 v33, v17, v17
	v_and_b32_e32 v17, 0xffff0000, v186
	v_fmac_f32_e32 v33, v17, v17
	v_lshlrev_b32_e32 v17, 16, v187
	v_fmac_f32_e32 v33, v17, v17
	v_and_b32_e32 v17, 0xffff0000, v187
	v_fmac_f32_e32 v33, v17, v17
	v_lshlrev_b32_e32 v17, 16, v188
	v_fmac_f32_e32 v33, v17, v17
	v_and_b32_e32 v17, 0xffff0000, v188
	v_fmac_f32_e32 v33, v17, v17
	v_lshlrev_b32_e32 v17, 16, v189
	v_fmac_f32_e32 v33, v17, v17
	v_and_b32_e32 v17, 0xffff0000, v189
	v_fmac_f32_e32 v33, v17, v17
	v_lshlrev_b32_e32 v17, 16, v190
	v_fmac_f32_e32 v33, v17, v17
	v_and_b32_e32 v17, 0xffff0000, v190
	v_fmac_f32_e32 v33, v17, v17
	v_add_f32_e32 v17, v26, v33
	v_add_f32_e32 v17, v27, v17
	v_mov_b32_e32 v26, v17
	s_nop 1
	v_permlane32_swap_b32_e32 v17, v26
	v_add_f32_e32 v17, v17, v26
	v_mul_f32_e32 v26, 0x4f800000, v17
	v_cmp_gt_f32_e32 vcc, s3, v17
	v_lshrrev_b32_e32 v32, 3, v31
	v_and_b32_e32 v27, 0xffffff8, v31
	v_cndmask_b32_e32 v17, v17, v26, vcc
	v_sqrt_f32_e32 v26, v17
	v_mul_lo_u32 v31, v32, s20
	v_sub_u32_e32 v27, v16, v27
	v_lshl_add_u32 v215, v27, 4, v31
	v_add_u32_e32 v32, -1, v26
	v_fma_f32 v33, -v32, v26, v17
	v_cmp_ge_f32_e64 s[4:5], 0, v33
	v_add_u32_e32 v33, 1, v26
	s_nop 0
	v_cndmask_b32_e64 v32, v26, v32, s[4:5]
	v_fma_f32 v26, -v33, v26, v17
	v_cmp_lt_f32_e64 s[4:5], 0, v26
	s_barrier
	s_nop 0
	v_cndmask_b32_e64 v26, v32, v33, s[4:5]
	v_mul_f32_e32 v32, 0x37800000, v26
	v_cndmask_b32_e32 v26, v26, v32, vcc
	v_cmp_class_f32_e32 vcc, v17, v220
	s_waitcnt vmcnt(3)
	ds_write_b128 v215, v[0:3]
	s_waitcnt vmcnt(2)
	ds_write_b128 v212, v[4:7] offset:18432
	s_waitcnt vmcnt(1)
	ds_write_b128 v214, v[8:11] offset:18432
	s_waitcnt vmcnt(0)
	ds_write_b128 v215, v[12:15] offset:9216
	v_cndmask_b32_e32 v17, v26, v17, vcc
	v_add_co_u32_e32 v0, vcc, s0, v20
	v_and_b32_e32 v2, 4, v29
	s_nop 0
	v_addc_co_u32_e32 v1, vcc, 0, v21, vcc
	global_load_dwordx4 v[192:195], v[0:1], off
	global_load_dwordx4 v[196:199], v[22:23], off offset:128
	global_load_dwordx4 v[200:203], v[24:25], off offset:128
	v_lshlrev_b32_e32 v1, 1, v16
	v_and_b32_e32 v0, 19, v16
	v_and_b32_e32 v1, 8, v1
	v_or3_b32 v0, v0, v1, v2
	v_mad_u32_u24 v225, v0, s20, v208
	s_waitcnt lgkmcnt(0)
	s_barrier
; __device__ __forceinline__ int swz23(int r) { return (r & ~12) | ((r & 4) << 1) | ((r & 8) >> 1); }
; #define LOADK(dst, t) do { _Pragma("unroll") for (int j = 0; j < NKC; ++j) if (j == 0 || k1) dst[j] = *(const u32x4*)(kh + (size_t)(((t) + rot) & (NT - 1)) * 64 * DQK + (size_t)(tid + 512 * j) * 8); } while (0)
; #define LOADV(dst, t) do { _Pragma("unroll") for (int j = 0; j < NVC; ++j) dst[j] = *(const u32x4*)(vg0 + (size_t)(64 * j) * S + (size_t)(((t) + rot) & (NT - 1)) * 64); } while (0)
; #define STOREK(src, slot) do { _Pragma("unroll") for (int j = 0; j < NKC; ++j) if (j == 0 || k1) *(u32x4*)(sK + (slot) * KSB + klo[j]) = src[j]; } while (0)
; #define STOREV(src, slot) do { _Pragma("unroll") for (int j = 0; j < NVC; ++j) *(u32x4*)(sV + (slot) * VSB + vlo[j]) = src[j]; } while (0)
; template <int DQK, int DV>
; __device__ __forceinline__ void attn_pass(const bf16_t* __restrict__ qh, const bf16_t* __restrict__ kh, const bf16_t* __restrict__ vth, int q0, char* smem, f32x16 (&o)[DV / 32], float kmax, int wvp) {
;     ...
;   for (int eb = 0; eb < NEB; ++eb)
; #pragma unroll
;     for (int i = 0; i < 16; ++i) o[eb][i] = 0.f;
;   float l_run = 0.f;
;   f32x16 negm;
;   {
;     float qq = 0.f;
; #pragma unroll
;     for (int ks = 0; ks < NKS; ++ks)
; #pragma unroll
;       for (int j = 0; j < 8; ++j) { const float t = bf2f((unsigned short)qf[ks][j]); qq += t * t; }
;     { auto rr = __builtin_amdgcn_permlane32_swap(__float_as_uint(qq), __float_as_uint(qq), false, false); qq = __uint_as_float(rr[0]) + __uint_as_float(rr[1]); }
;     const float mref = sqrtf(qq) * kmax * 1.01f + 0.01f;
; #pragma unroll
;     for (int i = 0; i < 16; ++i) negm[i] = -mref;
;   }
;   __syncthreads();
;   STOREK(rk, 0); STOREV(rv, 0); STOREK(rk1, 1);
;   LOADK(rk, 2); LOADV(rv, 1);
;   const int kofs = swz23(r) * KP + 16 * h, vofs = r * VP + 16 * h;
;   __syncthreads();
;   f32x16 sA, sB;
;     ...
;   f32x16 sA0, sA1, sB0, sB1;
;   QKT(sA, 0);
	ds_read_b128 v[0:3], v225
	ds_read_b128 v[4:7], v225 offset:32
	v_mul_f32_e32 v17, v30, v17
	v_fmamk_f32 v17, v17, 0x3f8147ae, v221
	v_xor_b32_e32 v64, 0x80000000, v17
	v_mov_b32_e32 v65, v64
	v_mov_b32_e32 v66, v64
	v_mov_b32_e32 v67, v64
	v_mov_b32_e32 v68, v64
	v_mov_b32_e32 v69, v64
	v_mov_b32_e32 v70, v64
	v_mov_b32_e32 v71, v64
	v_mov_b32_e32 v72, v64
	v_mov_b32_e32 v73, v64
	v_mov_b32_e32 v74, v64
	v_mov_b32_e32 v75, v64
	v_mov_b32_e32 v76, v64
	v_mov_b32_e32 v77, v64
	v_mov_b32_e32 v78, v64
	v_mov_b32_e32 v79, v64
	v_mov_b32_e32 v213, 0
	v_mad_u32_u24 v208, v28, s20, v208
	s_waitcnt lgkmcnt(1)
	v_mfma_f32_32x32x16_bf16 v[96:111], v[0:3], v[176:179], v[64:79]
	ds_read_b128 v[0:3], v225 offset:4608
	ds_read_b128 v[8:11], v225 offset:4640
	v_mov_b32_e32 v16, 0
	v_mov_b32_e32 v17, v213
	v_mov_b32_e32 v18, v213
	v_mov_b32_e32 v19, v213
	v_mov_b32_e32 v20, v213
	v_mov_b32_e32 v21, v213
	s_waitcnt lgkmcnt(2)
	v_mfma_f32_32x32x16_bf16 v[96:111], v[4:7], v[180:183], v[96:111]
	v_mov_b32_e32 v22, v213
	v_mov_b32_e32 v23, v213
	v_mov_b32_e32 v24, v213
	v_mov_b32_e32 v25, v213
	v_mov_b32_e32 v26, v213
	v_mov_b32_e32 v27, v213
	v_mov_b32_e32 v28, v213
	s_waitcnt lgkmcnt(1)
	v_mfma_f32_32x32x16_bf16 v[80:95], v[0:3], v[176:179], v[64:79]
	ds_read_b128 v[0:3], v225 offset:64
	ds_read_b128 v[4:7], v225 offset:96
	v_mov_b32_e32 v29, v213
	v_mov_b32_e32 v30, v213
	v_mov_b32_e32 v31, v213
	v_mov_b32_e32 v32, 0
	v_mov_b32_e32 v33, v213
	v_mov_b32_e32 v34, v213
	s_waitcnt lgkmcnt(1)
	v_mfma_f32_32x32x16_bf16 v[96:111], v[0:3], v[184:187], v[96:111]
	v_mov_b32_e32 v35, v213
	v_mov_b32_e32 v36, v213
	v_mov_b32_e32 v37, v213
	v_mov_b32_e32 v38, v213
	v_mov_b32_e32 v39, v213
	v_mov_b32_e32 v40, v213
	v_mov_b32_e32 v41, v213
	v_mfma_f32_32x32x16_bf16 v[80:95], v[8:11], v[180:183], v[80:95]
	v_mov_b32_e32 v42, v213
	v_mov_b32_e32 v43, v213
	v_mov_b32_e32 v44, v213
	v_mov_b32_e32 v45, v213
	v_mov_b32_e32 v46, v213
	v_mov_b32_e32 v47, v213
	v_mov_b32_e32 v49, v213
	s_waitcnt lgkmcnt(0)
	v_mfma_f32_32x32x16_bf16 v[96:111], v[4:7], v[188:191], v[96:111]
	ds_read_b128 v[0:3], v225 offset:4672
	ds_read_b128 v[4:7], v225 offset:4704
	v_mov_b32_e32 v50, v213
	v_mov_b32_e32 v51, v213
	v_mov_b32_e32 v52, v213
	v_mov_b32_e32 v53, v213
	v_mov_b32_e32 v54, v213
	v_mov_b32_e32 v55, v213
	s_waitcnt lgkmcnt(1)
	v_mfma_f32_32x32x16_bf16 v[80:95], v[0:3], v[184:187], v[80:95]
	v_mov_b32_e32 v56, v213
	v_mov_b32_e32 v57, v213
	v_mov_b32_e32 v58, v213
	v_mov_b32_e32 v59, v213
	v_mov_b32_e32 v60, v213
	v_mov_b32_e32 v61, v213
	v_mov_b32_e32 v62, v213
	s_waitcnt lgkmcnt(0)
	v_mfma_f32_32x32x16_bf16 v[80:95], v[4:7], v[188:191], v[80:95]
	v_mov_b32_e32 v63, v213
	v_mov_b32_e32 v0, 0
	v_mov_b32_e32 v1, v213
	v_mov_b32_e32 v2, v213
	v_mov_b32_e32 v3, v213
	v_mov_b32_e32 v4, v213
	v_mov_b32_e32 v5, v213
	v_mov_b32_e32 v6, v213
	v_mov_b32_e32 v7, v213
	v_mov_b32_e32 v8, v213
	v_mov_b32_e32 v9, v213
	v_mov_b32_e32 v10, v213
	v_mov_b32_e32 v11, v213
	v_mov_b32_e32 v12, v213
	v_mov_b32_e32 v13, v213
	v_mov_b32_e32 v14, v213
	v_mov_b32_e32 v15, v213
	s_cmpk_lt_u32 s18, 0x7c
	s_cbranch_scc0 .LBB0_597
.Lfast_e2:
	s_barrier
	s_waitcnt vmcnt(0)
	ds_write_b128 v215, v[192:195]
	s_waitcnt vmcnt(1)
	ds_write_b128 v212, v[196:199] offset:36864
	s_waitcnt vmcnt(0)
	ds_write_b128 v214, v[200:203] offset:36864
	s_add_i32 s4, s37, 0xfffff000
	s_and_b32 s4, s4, 0x7f000
	s_lshl_b32 s8, s4, 1
	v_lshl_add_u64 v[112:113], v[218:219], 0, s[8:9]
	global_load_dwordx4 v[192:195], v[112:113], off
	s_sub_i32 s6, s19, 64
	s_and_b32 s6, s6, 0x1f80
	s_lshl_b32 s8, s6, 1
	v_lshl_add_u64 v[112:113], v[216:217], 0, s[8:9]
	v_add_co_u32_e32 v114, vcc, 0x100000, v112
	s_nop 1
	v_addc_co_u32_e32 v115, vcc, 0, v113, vcc
	global_load_dwordx4 v[196:199], v[112:113], off
	global_load_dwordx4 v[200:203], v[114:115], off
	ds_read_b128 v[112:115], v225 offset:9216
	ds_read_b128 v[128:131], v225 offset:9248
	ds_read_b128 v[132:135], v225 offset:13824
	ds_read_b128 v[136:139], v225 offset:13856
	v_exp_f32_e32 v172, v92
	v_exp_f32_e32 v173, v93
	s_waitcnt lgkmcnt(3)
	v_mfma_f32_32x32x16_bf16 v[144:159], v[112:115], v[176:179], v[64:79]
	v_exp_f32_e32 v174, v94
	v_exp_f32_e32 v175, v95
	s_waitcnt lgkmcnt(2)
	v_mfma_f32_32x32x16_bf16 v[144:159], v[128:131], v[180:183], v[144:159]
	s_waitcnt lgkmcnt(1)
	v_mfma_f32_32x32x16_bf16 v[112:127], v[132:135], v[176:179], v[64:79]
	ds_read_b128 v[128:131], v225 offset:9280
	ds_read_b128 v[132:135], v225 offset:9312
	ds_read_b128 v[140:143], v225 offset:13888
	ds_read_b128 v[228:231], v225 offset:13920
	ds_read_b128 v[160:163], v208 offset:18464
	s_waitcnt lgkmcnt(4)
	v_mfma_f32_32x32x16_bf16 v[144:159], v[128:131], v[184:187], v[144:159]
	v_exp_f32_e32 v128, v96
	v_exp_f32_e32 v129, v97
	v_exp_f32_e32 v130, v98
	v_exp_f32_e32 v131, v99
	ds_read_b128 v[96:99], v208 offset:18432
	s_waitcnt lgkmcnt(4)
	v_mfma_f32_32x32x16_bf16 v[144:159], v[132:135], v[188:191], v[144:159]
	v_exp_f32_e32 v132, v100
	v_exp_f32_e32 v133, v101
	v_exp_f32_e32 v134, v102
	v_exp_f32_e32 v135, v103
	v_cvt_pk_bf16_f32 v100, v128, v129
	v_cvt_pk_bf16_f32 v101, v130, v131
	v_cvt_pk_bf16_f32 v102, v132, v133
	v_cvt_pk_bf16_f32 v103, v134, v135
	v_mfma_f32_32x32x16_bf16 v[112:127], v[136:139], v[180:183], v[112:127]
	v_exp_f32_e32 v136, v104
	v_exp_f32_e32 v137, v105
	v_exp_f32_e32 v138, v106
	v_exp_f32_e32 v139, v107
	s_waitcnt lgkmcnt(0)
	v_mfma_f32_32x32x16_bf16 v[0:15], v[96:99], v[100:103], v[0:15]
	ds_read_b128 v[96:99], v208 offset:23040
	ds_read_b128 v[164:167], v208 offset:23072
	s_waitcnt lgkmcnt(1)
; template <int DQK, int DV>
; __device__ __forceinline__ void attn_pass(const bf16_t* __restrict__ qh, const bf16_t* __restrict__ kh, const bf16_t* __restrict__ vth, int q0, char* smem, f32x16 (&o)[DV / 32], float kmax, int wvp) {
;     ...
; #pragma unroll
;   for (int ks = 0; ks < NKS; ++ks) asm volatile("" :: "v"(qf[ks]));
; #pragma unroll 1
;   for (int kt = 0; kt < NT; kt += 2) {
;     STEP(sA, sB, kt);
;     STEP(sB, sA, kt + 1);
	v_mfma_f32_32x32x16_bf16 v[48:63], v[96:99], v[100:103], v[48:63]
	ds_read_b128 v[96:99], v208 offset:27648
	ds_read_b128 v[168:171], v208 offset:27680
	ds_read_b128 v[104:107], v208 offset:32288
	s_waitcnt lgkmcnt(2)
	v_mfma_f32_32x32x16_bf16 v[32:47], v[96:99], v[100:103], v[32:47]
	ds_read_b128 v[96:99], v208 offset:32256
	v_mfma_f32_32x32x16_bf16 v[112:127], v[140:143], v[184:187], v[112:127]
	v_exp_f32_e32 v140, v108
	v_exp_f32_e32 v141, v109
	v_exp_f32_e32 v142, v110
	v_exp_f32_e32 v143, v111
	s_waitcnt lgkmcnt(0)
	v_mfma_f32_32x32x16_bf16 v[16:31], v[96:99], v[100:103], v[16:31]
	v_cvt_pk_bf16_f32 v96, v136, v137
	v_cvt_pk_bf16_f32 v97, v138, v139
	v_cvt_pk_bf16_f32 v98, v140, v141
	v_cvt_pk_bf16_f32 v99, v142, v143
	s_nop 1
	v_mfma_f32_32x32x16_bf16 v[0:15], v[160:163], v[96:99], v[0:15]
	v_exp_f32_e32 v160, v80
	v_exp_f32_e32 v161, v81
	v_exp_f32_e32 v162, v82
	v_exp_f32_e32 v163, v83
	ds_read_b128 v[80:83], v208 offset:18496
	v_mfma_f32_32x32x16_bf16 v[48:63], v[164:167], v[96:99], v[48:63]
	v_exp_f32_e32 v164, v84
	v_exp_f32_e32 v165, v85
	v_exp_f32_e32 v166, v86
	v_exp_f32_e32 v167, v87
	v_cvt_pk_bf16_f32 v84, v160, v161
	v_cvt_pk_bf16_f32 v85, v162, v163
	v_cvt_pk_bf16_f32 v86, v164, v165
	v_cvt_pk_bf16_f32 v87, v166, v167
	v_mfma_f32_32x32x16_bf16 v[32:47], v[168:171], v[96:99], v[32:47]
	v_exp_f32_e32 v168, v88
	v_exp_f32_e32 v169, v89
	v_exp_f32_e32 v170, v90
	v_exp_f32_e32 v171, v91
	v_mfma_f32_32x32x16_bf16 v[16:31], v[104:107], v[96:99], v[16:31]
	ds_read_b128 v[96:99], v208 offset:18528
	s_waitcnt lgkmcnt(1)
	v_mfma_f32_32x32x16_bf16 v[0:15], v[80:83], v[84:87], v[0:15]
	ds_read_b128 v[80:83], v208 offset:23104
	ds_read_b128 v[100:103], v208 offset:23136
	s_waitcnt lgkmcnt(1)
	v_mfma_f32_32x32x16_bf16 v[48:63], v[80:83], v[84:87], v[48:63]
	ds_read_b128 v[80:83], v208 offset:27712
	ds_read_b128 v[104:107], v208 offset:27744
	ds_read_b128 v[88:91], v208 offset:32352
	s_waitcnt lgkmcnt(2)
	v_mfma_f32_32x32x16_bf16 v[32:47], v[80:83], v[84:87], v[32:47]
	ds_read_b128 v[80:83], v208 offset:32320
	s_waitcnt lgkmcnt(0)
	s_barrier
	v_mfma_f32_32x32x16_bf16 v[16:31], v[80:83], v[84:87], v[16:31]
	v_cvt_pk_bf16_f32 v80, v168, v169
	v_cvt_pk_bf16_f32 v81, v170, v171
	v_cvt_pk_bf16_f32 v82, v172, v173
	v_cvt_pk_bf16_f32 v83, v174, v175
	s_nop 1
	v_mfma_f32_32x32x16_bf16 v[0:15], v[96:99], v[80:83], v[0:15]
	v_mfma_f32_32x32x16_bf16 v[48:63], v[100:103], v[80:83], v[48:63]
	v_mfma_f32_32x32x16_bf16 v[32:47], v[104:107], v[80:83], v[32:47]
	v_mfma_f32_32x32x16_bf16 v[16:31], v[88:91], v[80:83], v[16:31]
	v_mfma_f32_32x32x16_bf16 v[112:127], v[228:231], v[188:191], v[112:127]
	s_waitcnt vmcnt(0)
	ds_write_b128 v215, v[192:195] offset:9216
	s_waitcnt vmcnt(1)
	ds_write_b128 v212, v[196:199] offset:18432
	s_waitcnt vmcnt(0)
	ds_write_b128 v214, v[200:203] offset:18432
	s_and_b32 s8, s37, 0x7e000
	s_lshl_b32 s8, s8, 1
	v_lshl_add_u64 v[80:81], v[218:219], 0, s[8:9]
	global_load_dwordx4 v[192:195], v[80:81], off
	s_and_b32 s6, s19, 0x1fc0
	s_lshl_b32 s8, s6, 1
	v_lshl_add_u64 v[80:81], v[216:217], 0, s[8:9]
	v_add_co_u32_e32 v82, vcc, 0x100000, v80
	s_nop 1
	v_addc_co_u32_e32 v83, vcc, 0, v81, vcc
	global_load_dwordx4 v[196:199], v[80:81], off
	global_load_dwordx4 v[200:203], v[82:83], off
	ds_read_b128 v[80:83], v225
	ds_read_b128 v[228:231], v225 offset:32
	ds_read_b128 v[232:235], v225 offset:4608
	ds_read_b128 v[236:239], v225 offset:4640
	s_waitcnt lgkmcnt(3)
	v_mfma_f32_32x32x16_bf16 v[96:111], v[80:83], v[176:179], v[64:79]
	s_waitcnt lgkmcnt(1)
	v_mfma_f32_32x32x16_bf16 v[80:95], v[232:235], v[176:179], v[64:79]
	v_mfma_f32_32x32x16_bf16 v[96:111], v[228:231], v[180:183], v[96:111]
	ds_read_b128 v[228:231], v225 offset:64
	ds_read_b128 v[232:235], v225 offset:96
	s_waitcnt lgkmcnt(2)
	v_mfma_f32_32x32x16_bf16 v[80:95], v[236:239], v[180:183], v[80:95]
	s_waitcnt lgkmcnt(1)
	v_mfma_f32_32x32x16_bf16 v[96:111], v[228:231], v[184:187], v[96:111]
	ds_read_b128 v[228:231], v225 offset:4672
	ds_read_b128 v[236:239], v225 offset:4704
	s_waitcnt lgkmcnt(1)
	v_mfma_f32_32x32x16_bf16 v[80:95], v[228:231], v[184:187], v[80:95]
	v_mfma_f32_32x32x16_bf16 v[96:111], v[232:235], v[188:191], v[96:111]
	s_waitcnt lgkmcnt(0)
	v_mfma_f32_32x32x16_bf16 v[80:95], v[236:239], v[188:191], v[80:95]
	v_exp_f32_e32 v227, v144
	v_exp_f32_e32 v248, v145
	v_exp_f32_e32 v249, v146
	v_exp_f32_e32 v250, v147
	ds_read_b128 v[144:147], v208 offset:36864
	v_exp_f32_e32 v240, v148
	v_exp_f32_e32 v242, v149
	v_exp_f32_e32 v244, v150
	v_exp_f32_e32 v246, v151
	v_cvt_pk_bf16_f32 v148, v227, v248
	v_cvt_pk_bf16_f32 v149, v249, v250
	v_cvt_pk_bf16_f32 v150, v240, v242
	v_cvt_pk_bf16_f32 v151, v244, v246
	ds_read_b128 v[228:231], v208 offset:36896
	ds_read_b128 v[232:235], v208 offset:41472
	s_waitcnt lgkmcnt(2)
	v_mfma_f32_32x32x16_bf16 v[0:15], v[144:147], v[148:151], v[0:15]
	v_add_f32_e32 v128, v129, v128
	v_add_f32_e32 v129, v161, v160
	ds_read_b128 v[144:147], v208 offset:46080
	ds_read_b128 v[236:239], v208 offset:41504
	v_add_f32_e32 v128, v130, v128
	v_add_f32_e32 v129, v162, v129
	v_add_f32_e32 v128, v131, v128
	v_add_f32_e32 v129, v163, v129
	s_waitcnt lgkmcnt(2)
; template <int DQK, int DV>
; __device__ __forceinline__ void attn_pass(const bf16_t* __restrict__ qh, const bf16_t* __restrict__ kh, const bf16_t* __restrict__ vth, int q0, char* smem, f32x16 (&o)[DV / 32], float kmax, int wvp) {
;     ...
; #pragma unroll
;   for (int ks = 0; ks < NKS; ++ks) asm volatile("" :: "v"(qf[ks]));
; #pragma unroll 1
;   for (int kt = 0; kt < NT; kt += 2) {
;     STEP(sA, sB, kt);
;     STEP(sB, sA, kt + 1);
;   }
	v_mfma_f32_32x32x16_bf16 v[48:63], v[232:235], v[148:151], v[48:63]
	v_add_f32_e32 v132, v132, v128
	v_add_f32_e32 v233, v164, v129
	ds_read_b128 v[128:131], v208 offset:50688
	ds_read_b128 v[160:163], v208 offset:46112
	v_exp_f32_e32 v152, v152
	v_exp_f32_e32 v164, v153
	v_exp_f32_e32 v154, v154
	v_exp_f32_e32 v232, v155
	s_waitcnt lgkmcnt(3)
	v_mfma_f32_32x32x16_bf16 v[32:47], v[144:147], v[148:151], v[32:47]
	v_exp_f32_e32 v156, v156
	ds_read_b128 v[144:147], v208 offset:50720
	v_add_f32_e32 v132, v133, v132
	v_add_f32_e32 v133, v165, v233
	v_add_f32_e32 v133, v166, v133
	v_exp_f32_e32 v166, v112
	v_add_f32_e32 v132, v134, v132
	s_waitcnt lgkmcnt(2)
	v_mfma_f32_32x32x16_bf16 v[16:31], v[128:131], v[148:151], v[16:31]
	v_exp_f32_e32 v148, v157
	v_exp_f32_e32 v150, v158
	v_exp_f32_e32 v158, v159
	v_cvt_pk_bf16_f32 v128, v152, v164
	v_cvt_pk_bf16_f32 v129, v154, v232
	v_cvt_pk_bf16_f32 v130, v156, v148
	v_cvt_pk_bf16_f32 v131, v150, v158
	v_add_f32_e32 v132, v135, v132
	v_add_f32_e32 v133, v167, v133
	s_waitcnt lgkmcnt(1)
	v_mfma_f32_32x32x16_bf16 v[32:47], v[160:163], v[128:131], v[32:47]
	v_exp_f32_e32 v160, v113
	v_exp_f32_e32 v161, v114
	v_exp_f32_e32 v162, v115
	ds_read_b128 v[112:115], v208 offset:36928
	v_add_f32_e32 v132, v136, v132
	v_add_f32_e32 v133, v168, v133
	v_exp_f32_e32 v241, v116
	v_mfma_f32_32x32x16_bf16 v[0:15], v[228:231], v[128:131], v[0:15]
	v_exp_f32_e32 v243, v117
	v_exp_f32_e32 v245, v118
	v_exp_f32_e32 v247, v119
	v_add_f32_e32 v132, v137, v132
	v_add_f32_e32 v133, v169, v133
	v_add_f32_e32 v132, v138, v132
	v_add_f32_e32 v133, v170, v133
	v_mfma_f32_32x32x16_bf16 v[48:63], v[236:239], v[128:131], v[48:63]
	v_add_f32_e32 v136, v139, v132
	v_add_f32_e32 v137, v171, v133
	v_cvt_pk_bf16_f32 v116, v166, v160
	v_cvt_pk_bf16_f32 v117, v161, v162
	v_cvt_pk_bf16_f32 v118, v241, v243
	v_cvt_pk_bf16_f32 v119, v245, v247
	v_exp_f32_e32 v153, v120
	s_waitcnt lgkmcnt(1)
	v_mfma_f32_32x32x16_bf16 v[16:31], v[144:147], v[128:131], v[16:31]
	ds_read_b128 v[128:131], v208 offset:41536
	ds_read_b128 v[132:135], v208 offset:36960
	v_exp_f32_e32 v165, v121
	v_add_f32_e32 v120, v248, v227
	v_add_f32_e32 v121, v160, v166
	v_add_f32_e32 v120, v249, v120
	s_waitcnt lgkmcnt(2)
	v_mfma_f32_32x32x16_bf16 v[0:15], v[112:115], v[116:119], v[0:15]
	v_add_f32_e32 v112, v140, v136
	v_add_f32_e32 v113, v172, v137
	v_add_f32_e32 v112, v141, v112
	v_add_f32_e32 v140, v173, v113
	v_add_f32_e32 v141, v142, v112
	ds_read_b128 v[112:115], v208 offset:46144
	ds_read_b128 v[136:139], v208 offset:41568
	v_add_f32_e32 v121, v161, v121
	s_waitcnt lgkmcnt(3)
	v_mfma_f32_32x32x16_bf16 v[48:63], v[128:131], v[116:119], v[48:63]
	v_add_f32_e32 v128, v174, v140
	v_add_f32_e32 v129, v143, v141
	v_add_f32_e32 v128, v175, v128
	v_add_f32_e32 v128, v129, v128
	v_add_f32_e32 v144, v213, v128
	ds_read_b128 v[128:131], v208 offset:50752
	ds_read_b128 v[140:143], v208 offset:46176
	v_add_f32_e32 v120, v250, v120
	s_waitcnt lgkmcnt(3)
	v_mfma_f32_32x32x16_bf16 v[32:47], v[112:115], v[116:119], v[32:47]
	ds_read_b128 v[112:115], v208 offset:50784
	v_add_f32_e32 v121, v162, v121
	v_add_f32_e64 v120, v240, v120
	v_add_f32_e64 v121, v241, v121
	v_exp_f32_e32 v155, v122
	v_exp_f32_e32 v233, v123
	v_exp_f32_e32 v157, v124
	v_exp_f32_e32 v149, v125
	s_waitcnt lgkmcnt(2)
	v_mfma_f32_32x32x16_bf16 v[16:31], v[128:131], v[116:119], v[16:31]
	v_exp_f32_e32 v151, v126
	v_exp_f32_e32 v159, v127
	v_add_f32_e32 v120, v242, v120
	v_add_f32_e32 v121, v243, v121
	v_cvt_pk_bf16_f32 v116, v153, v165
	v_add_f32_e32 v120, v244, v120
	v_add_f32_e32 v121, v245, v121
	v_cvt_pk_bf16_f32 v117, v155, v233
	v_add_f32_e32 v120, v246, v120
	v_add_f32_e32 v121, v247, v121
	v_cvt_pk_bf16_f32 v118, v157, v149
	v_add_f32_e32 v120, v152, v120
	v_add_f32_e32 v121, v153, v121
	v_cvt_pk_bf16_f32 v119, v151, v159
	v_add_f32_e32 v120, v164, v120
	v_add_f32_e32 v121, v165, v121
	s_add_i32 s18, s18, 2
	v_mfma_f32_32x32x16_bf16 v[0:15], v[132:135], v[116:119], v[0:15]
	v_add_f32_e64 v120, v154, v120
	v_add_f32_e64 v121, v155, v121
	s_addk_i32 s37, 0x2000
	v_add_f32_e64 v120, v232, v120
	v_add_f32_e64 v121, v233, v121
	v_add_f32_e32 v120, v156, v120
	v_add_f32_e32 v121, v157, v121
	s_addk_i32 s19, 0x80
	v_add_f32_e32 v120, v148, v120
	v_add_f32_e32 v121, v149, v121
	v_mfma_f32_32x32x16_bf16 v[48:63], v[136:139], v[116:119], v[48:63]
	v_add_f32_e64 v120, v150, v120
	v_add_f32_e64 v121, v151, v121
	v_add_f32_e64 v120, v158, v120
	v_add_f32_e64 v121, v159, v121
	v_add_f32_e32 v120, v120, v121
	v_add_f32_e32 v213, v144, v120
	s_waitcnt lgkmcnt(1)
	v_mfma_f32_32x32x16_bf16 v[32:47], v[140:143], v[116:119], v[32:47]
	s_waitcnt lgkmcnt(0)
	v_mfma_f32_32x32x16_bf16 v[16:31], v[112:115], v[116:119], v[16:31]
	s_cmpk_lt_u32 s18, 0x7c
	s_cbranch_scc1 .Lfast_e2
	s_branch .LBB0_597
